# EW phase chunk-scalar unit: its three distinct global loads issued together (one wait) instead of four serial round trips
# speedup vs baseline: 1.0069x; 1.0069x over previous
; __device__ __forceinline__ float frcp(float x) { return __builtin_amdgcn_rcpf(x); }
; __device__ __forceinline__ float fexp(float x) { return __builtin_amdgcn_exp2f(x * 1.4426950408889634f); }
; __device__ __forceinline__ float logsigf_(float x) { return x >= 0.f ? -flog1p(fexp(-x)) : x - flog1p(fexp(x)); }
; __device__ __forceinline__ float flog1p(float y) { return y < 0.02f ? y * (1.0f - y * (0.5f - y * (0.33333333f - 0.25f * y))) : __builtin_amdgcn_logf(1.0f + y) * 0.6931471805599453f; }
; __device__ __forceinline__ float sigmoidf_(float x) { return frcp(1.f + fexp(-x)); }
; __device__ __forceinline__ float siluf_(float x) { return x * frcp(1.f + fexp(-x)); }
; __device__ __forceinline__ float softplusf_(float x) { return x > 20.f ? x : flog1p(fexp(x)); }
; __device__ __forceinline__ void chs_unit(const Frame& F, int l, int ck) {
;     ...
;     for (int j = 0; j < 2; ++j) { const int idx = t + 512 * j, p = idx >> 4, c = idx & 15, dh = c & 7;
;         const float raw = bf2f(F.Z[(size_t)(row0 + p) * ZW + ZC_LI + c]);
;         G[c * 64 + p] = c < 8 ? raw + F.ig_bias[l * 8 + dh] : logsigf_(raw + F.fg_bias[l * 8 + dh]); }
.LBB0_772:
	v_mbcnt_lo_u32_b32 v6, -1, 0
	v_mbcnt_hi_u32_b32 v6, -1, v6
	v_mov_b64_e32 v[2:3], s[16:17]
	v_add_u32_e32 v7, s64, v6
	v_ashrrev_i32_e32 v9, 4, v7
	v_and_b32_e32 v8, 15, v6
	v_add_u32_e32 v0, s8, v9
	v_mad_i64_i32 v[2:3], s[12:13], v0, s66, v[2:3]
	v_lshlrev_b32_e32 v0, 1, v8
	v_lshl_add_u64 v[2:3], v[2:3], 0, v[0:1]
	v_add_co_u32_e32 v2, vcc, 0x1000, v2
	v_cmp_lt_u32_e64 s[38:39], 7, v8
	s_nop 0
	v_addc_co_u32_e32 v3, vcc, 0, v3, vcc
	global_load_ushort v10, v[2:3], off offset:2080
	v_and_or_b32 v2, v6, 7, s68
	v_ashrrev_i32_e32 v3, 31, v2
	v_lshlrev_b64 v[4:5], 2, v[2:3]
	v_lshl_add_u64 v[2:3], s[44:45], 0, v[4:5]
	v_add_u32_e32 v178, 0x200, v7
	v_ashrrev_i32_e32 v178, 4, v178
	v_add_u32_e32 v178, s8, v178
	v_mov_b64_e32 v[180:181], s[16:17]
	v_mad_i64_i32 v[180:181], s[12:13], v178, s66, v[180:181]
	v_lshl_add_u64 v[180:181], v[180:181], 0, v[0:1]
	s_movk_i32 s12, 0x1000
	s_mov_b32 s13, 0
	v_lshl_add_u64 v[180:181], v[180:181], 0, s[12:13]
	global_load_ushort v184, v[180:181], off offset:2080
	v_lshl_add_u64 v[182:183], s[42:43], 0, v[4:5]
	s_mov_b64 s[12:13], exec
	s_and_b64 exec, s[12:13], s[38:39]
	global_load_dword v185, v[2:3], off
	s_andn2_b64 exec, s[12:13], s[38:39]
	global_load_dword v185, v[182:183], off
	s_mov_b64 exec, s[12:13]
	s_waitcnt vmcnt(0)
	v_lshlrev_b32_e32 v10, 16, v10
	s_and_saveexec_b64 s[12:13], s[38:39]
	s_xor_b64 s[20:21], exec, s[12:13]
	s_cbranch_execz .LBB0_786
	v_add_f32_e32 v10, v185, v10
	v_cmp_le_f32_e32 vcc, 0, v10
	s_and_saveexec_b64 s[12:13], vcc
	s_xor_b64 s[12:13], exec, s[12:13]
	s_cbranch_execz .LBB0_779
	v_mul_f32_e32 v10, 0xbfb8aa3b, v10
	v_exp_f32_e32 v10, v10
	s_mov_b32 s9, 0x3ca3d70a
	v_cmp_ngt_f32_e32 vcc, s9, v10
	s_and_saveexec_b64 s[14:15], vcc
	s_xor_b64 s[14:15], exec, s[14:15]
	v_add_f32_e32 v10, 1.0, v10
	v_log_f32_e32 v10, v10
	s_nop 0
	v_mul_f32_e32 v11, 0x3f317218, v10
	s_andn2_saveexec_b64 s[14:15], s[14:15]
	v_fmamk_f32 v11, v10, 0xbe800000, v222
	v_fma_f32 v11, -v10, v11, 0.5
	v_fma_f32 v11, -v10, v11, 1.0
	v_mul_f32_e32 v11, v10, v11
	s_or_b64 exec, exec, s[14:15]
	v_xor_b32_e32 v11, 0x80000000, v11

; __device__ __forceinline__ float logsigf_(float x) { return x >= 0.f ? -flog1p(fexp(-x)) : x - flog1p(fexp(x)); }
; __device__ __forceinline__ void chs_unit(const Frame& F, int l, int ck) {
;     ...
;     for (int j = 0; j < 2; ++j) { const int idx = t + 512 * j, p = idx >> 4, c = idx & 15, dh = c & 7;
;         const float raw = bf2f(F.Z[(size_t)(row0 + p) * ZW + ZC_LI + c]);
;         G[c * 64 + p] = c < 8 ? raw + F.ig_bias[l * 8 + dh] : logsigf_(raw + F.fg_bias[l * 8 + dh]); }
.LBB0_786:
	s_or_saveexec_b64 s[12:13], s[20:21]
	v_lshl_add_u64 v[4:5], s[42:43], 0, v[4:5]
	s_xor_b64 exec, exec, s[12:13]
	s_cbranch_execz .LBB0_788
	v_add_f32_e32 v11, v185, v10
.LBB0_788:
	s_or_b64 exec, exec, s[12:13]
	v_lshl_add_u32 v8, v8, 8, 0
	v_lshl_add_u32 v9, v9, 2, v8
	ds_write_b32 v9, v11
	v_add_u32_e32 v9, 0x200, v7
	v_ashrrev_i32_e32 v9, 4, v9
	v_add_u32_e32 v12, s8, v9
	v_mov_b64_e32 v[10:11], s[16:17]
	v_mad_i64_i32 v[10:11], s[8:9], v12, s66, v[10:11]
	v_lshl_add_u64 v[10:11], v[10:11], 0, v[0:1]
	v_add_co_u32_e32 v10, vcc, 0x1000, v10
	s_nop 1
	v_addc_co_u32_e32 v11, vcc, 0, v11, vcc
	v_lshlrev_b32_e32 v0, 16, v184
	s_and_saveexec_b64 s[8:9], s[38:39]
	s_xor_b64 s[20:21], exec, s[8:9]
	s_cbranch_execz .LBB0_802
	v_add_f32_e32 v0, v185, v0
	v_cmp_le_f32_e32 vcc, 0, v0
	s_and_saveexec_b64 s[8:9], vcc
	s_xor_b64 s[12:13], exec, s[8:9]
	s_cbranch_execz .LBB0_795
	v_mul_f32_e32 v0, 0xbfb8aa3b, v0
	v_exp_f32_e32 v0, v0
	s_mov_b32 s8, 0x3ca3d70a
	v_cmp_ngt_f32_e32 vcc, s8, v0
	s_and_saveexec_b64 s[8:9], vcc
	s_xor_b64 s[14:15], exec, s[8:9]
	v_add_f32_e32 v0, 1.0, v0
	v_log_f32_e32 v0, v0
	s_nop 0
	v_mul_f32_e32 v2, 0x3f317218, v0
	s_andn2_saveexec_b64 s[14:15], s[14:15]
	v_fmamk_f32 v2, v0, 0xbe800000, v222
	v_fma_f32 v2, -v0, v2, 0.5
	v_fma_f32 v2, -v0, v2, 1.0
	v_mul_f32_e32 v2, v0, v2
	s_or_b64 exec, exec, s[14:15]
	v_xor_b32_e32 v10, 0x80000000, v2

; __device__ __forceinline__ float logsigf_(float x) { return x >= 0.f ? -flog1p(fexp(-x)) : x - flog1p(fexp(x)); }
; __device__ __forceinline__ void chs_unit(const Frame& F, int l, int ck) {
;     ...
;     for (int j = 0; j < 2; ++j) { const int idx = t + 512 * j, p = idx >> 4, c = idx & 15, dh = c & 7;
;         const float raw = bf2f(F.Z[(size_t)(row0 + p) * ZW + ZC_LI + c]);
;         G[c * 64 + p] = c < 8 ? raw + F.ig_bias[l * 8 + dh] : logsigf_(raw + F.fg_bias[l * 8 + dh]); }
.LBB0_802:
	s_andn2_saveexec_b64 s[12:13], s[20:21]
	s_cbranch_execz .LBB0_804
	v_add_f32_e32 v10, v185, v0
